# GEMM K loop: first trip peeled, first-touch MFMAs use C=0, accumulator clear removed
# speedup vs baseline: 1.0120x; 1.0120x over previous
; #define PG8_STAGE(bufoff, gbase, voff) do { _Pragma("unroll") for (int _i = 0; _i < 2; ++_i) \
;         __builtin_amdgcn_global_load_lds((const unsigned*)((const char*)(gbase) + (voff)[_i]), (LAS unsigned*)(lds + (bufoff) + ldsw + _i * 8192), 16, 0, 0); } while (0)
; #define PG8_LDA(dst, b, h) do { _Pragma("unroll") for (int m = 0; m < 4; ++m) _Pragma("unroll") for (int k = 0; k < 2; ++k) dst[m][k] = *(const LAS bf16x8*)(lds + PG8_SA(b, h) + aoff + m * 2048 + k * 1024); } while (0)
; #define PG8_LDB(dst, b, h) do { _Pragma("unroll") for (int n = 0; n < 2; ++n) _Pragma("unroll") for (int k = 0; k < 2; ++k) dst[n][k] = *(const LAS bf16x8*)(lds + PG8_SB(b, h) + boff + n * 2048 + k * 1024); } while (0)
; #define PG8_WAIT_V(n) asm volatile("s_waitcnt vmcnt(" #n ")" ::: "memory")
; #define PG8_BAR __builtin_amdgcn_s_barrier()
; template <class Epi, class Sched>
; __device__ __forceinline__ void gemm_phase(LAS unsigned char* lds, const Gemm g, const Sched& S, const Epi& E, const int tid) {
;     ...
;         for (int t = 0; t < nt; t += 2) {
;             const bool last = (t == nt - 2);
;             const char* a1 = cA + (size_t)(t + 1) * kstep;
;             const char* a2 = last ? nA : cA + (size_t)(t + 2) * kstep; const char* b2 = last ? nB : cB + (size_t)(t + 2) * kstep;
;             const char* a3 = a2 + kstep; const char* b3 = b2 + kstep;
;             PG8_LDB(B0, 0, 0); PG8_LDB(B1, 0, 1); PG8_SCHED; PG8_LDA(At, 0, 0); PG8_STAGE(PG8_SA(1, 1), a1 + hstep, voffA);
;             PG8_WAIT_V(8); PG8_WAIT_L(0); PG8_BAR; PG8_MMA(0, 0, At, B0); PG8_MMA(0, 1, At, B1); PG8_BAR; PG8_SCHED;
;             PG8_LDA(At, 0, 1); PG8_STAGE(PG8_SB(0, 0), b2, voffB); PG8_STAGE(PG8_SB(0, 1), b2 + hstep, voffB); PG8_STAGE(PG8_SA(0, 0), a2, voffA);
;             PG8_WAIT_V(8); PG8_WAIT_L(0); PG8_BAR; PG8_MMA(1, 0, At, B0); PG8_MMA(1, 1, At, B1); PG8_BAR; PG8_SCHED;
;             PG8_LDB(B0, 1, 0); PG8_LDB(B1, 1, 1); PG8_SCHED; PG8_LDA(At, 1, 0); PG8_STAGE(PG8_SA(0, 1), a2 + hstep, voffA);
;             PG8_WAIT_V(8); PG8_WAIT_L(0); PG8_BAR; PG8_MMA(0, 0, At, B0); PG8_MMA(0, 1, At, B1); PG8_BAR; PG8_SCHED;
;             PG8_LDA(At, 1, 1); PG8_STAGE(PG8_SB(1, 0), b3, voffB); PG8_STAGE(PG8_SB(1, 1), b3 + hstep, voffB); PG8_STAGE(PG8_SA(1, 0), a3, voffA);
;             PG8_WAIT_V(8); PG8_WAIT_L(0); PG8_BAR; PG8_MMA(1, 0, At, B0); PG8_MMA(1, 1, At, B1); PG8_BAR; PG8_SCHED;
.LBB0_243:
	s_add_u32 s28, s12, 0x100
	s_addc_u32 s29, s13, 0
	s_add_u32 s10, s14, 0x80
	s_addc_u32 s11, s15, 0
	s_mov_b32 s12, 0
	s_add_i32 s14, s12, 2
	s_add_u32 s15, s10, 0x80
	s_addc_u32 s13, s11, 0
	s_add_i32 s39, 0, 0x10000
	s_cmp_eq_u32 s43, s12
	s_cselect_b32 s13, s35, s13
	s_cselect_b32 s12, s34, s15
	s_cselect_b32 s55, s87, s29
	s_cselect_b32 s54, s86, s28
	s_add_i32 s15, 0, 0x14000
	v_add_u32_e32 v140, s39, v202
	v_add_u32_e32 v144, s15, v202
	ds_read_b128 v[128:131], v140
	ds_read_b128 v[132:135], v140 offset:1024
	ds_read_b128 v[136:139], v140 offset:2048
	ds_read_b128 v[140:143], v140 offset:3072
	ds_read_b128 v[166:169], v144
	ds_read_b128 v[170:173], v144 offset:1024
	ds_read_b128 v[174:177], v144 offset:2048
	ds_read_b128 v[178:181], v144 offset:3072
	v_lshl_add_u64 v[232:233], s[10:11], 0, v[164:165]
	s_add_i32 m0, s70, 0xc000
	ds_read_b128 v[182:185], v203
	ds_read_b128 v[204:207], v203 offset:1024
	ds_read_b128 v[208:211], v203 offset:2048
	ds_read_b128 v[212:215], v203 offset:3072
	ds_read_b128 v[216:219], v203 offset:4096
	ds_read_b128 v[220:223], v203 offset:5120
	ds_read_b128 v[224:227], v203 offset:6144
	ds_read_b128 v[228:231], v203 offset:7168
	global_load_lds_dwordx4 v[232:233], off
	v_lshl_add_u64 v[232:233], s[10:11], 0, v[162:163]
	s_add_i32 m0, s70, 0xe000
	s_nop 0
	global_load_lds_dwordx4 v[232:233], off
	s_waitcnt vmcnt(8)
	s_waitcnt lgkmcnt(0)
	s_barrier
	s_setprio 1
	s_waitcnt lgkmcnt(0)
	v_mfma_f32_16x16x32_bf16 v[124:127], v[128:131], v[182:185], 0
	v_mfma_f32_16x16x32_bf16 v[120:123], v[136:139], v[182:185], 0
	v_mfma_f32_16x16x32_bf16 v[108:111], v[128:131], v[208:211], 0
	v_mfma_f32_16x16x32_bf16 v[104:107], v[136:139], v[208:211], 0
	v_mfma_f32_16x16x32_bf16 v[92:95], v[128:131], v[216:219], 0
	v_mfma_f32_16x16x32_bf16 v[88:91], v[136:139], v[216:219], 0
	v_mfma_f32_16x16x32_bf16 v[76:79], v[128:131], v[224:227], 0
	v_mfma_f32_16x16x32_bf16 v[72:75], v[136:139], v[224:227], 0
	v_mfma_f32_16x16x32_bf16 v[124:127], v[132:135], v[204:207], v[124:127]
	v_mfma_f32_16x16x32_bf16 v[120:123], v[140:143], v[204:207], v[120:123]
	v_mfma_f32_16x16x32_bf16 v[108:111], v[132:135], v[212:215], v[108:111]
	v_mfma_f32_16x16x32_bf16 v[104:107], v[140:143], v[212:215], v[104:107]
	v_mfma_f32_16x16x32_bf16 v[92:95], v[132:135], v[220:223], v[92:95]
	v_mfma_f32_16x16x32_bf16 v[88:91], v[140:143], v[220:223], v[88:91]
	v_mfma_f32_16x16x32_bf16 v[76:79], v[132:135], v[228:231], v[76:79]
	v_mfma_f32_16x16x32_bf16 v[72:75], v[140:143], v[228:231], v[72:75]
	s_setprio 0
	s_setprio 1
	v_mfma_f32_16x16x32_bf16 v[116:119], v[166:169], v[182:185], 0
	v_mfma_f32_16x16x32_bf16 v[112:115], v[174:177], v[182:185], 0
	v_mfma_f32_16x16x32_bf16 v[100:103], v[166:169], v[208:211], 0
	v_mfma_f32_16x16x32_bf16 v[96:99], v[174:177], v[208:211], 0
	v_mfma_f32_16x16x32_bf16 v[84:87], v[166:169], v[216:219], 0
	v_mfma_f32_16x16x32_bf16 v[80:83], v[174:177], v[216:219], 0
	v_mfma_f32_16x16x32_bf16 v[68:71], v[166:169], v[224:227], 0
	v_mfma_f32_16x16x32_bf16 v[64:67], v[174:177], v[224:227], 0
	v_mfma_f32_16x16x32_bf16 v[116:119], v[170:173], v[204:207], v[116:119]
	v_mfma_f32_16x16x32_bf16 v[112:115], v[178:181], v[204:207], v[112:115]
	v_mfma_f32_16x16x32_bf16 v[100:103], v[170:173], v[212:215], v[100:103]
	v_mfma_f32_16x16x32_bf16 v[96:99], v[178:181], v[212:215], v[96:99]
	v_mfma_f32_16x16x32_bf16 v[84:87], v[170:173], v[220:223], v[84:87]
	v_mfma_f32_16x16x32_bf16 v[80:83], v[178:181], v[220:223], v[80:83]
	v_mfma_f32_16x16x32_bf16 v[68:71], v[170:173], v[228:231], v[68:71]
	v_mfma_f32_16x16x32_bf16 v[64:67], v[178:181], v[228:231], v[64:67]
	s_setprio 0
	s_barrier
	s_add_i32 s39, s39, s25
	v_lshl_add_u64 v[232:233], s[54:55], 0, v[152:153]
	s_mov_b32 m0, s39
	ds_read_b128 v[182:185], v203 offset:16384
	ds_read_b128 v[204:207], v203 offset:17408
	ds_read_b128 v[208:211], v203 offset:18432
	ds_read_b128 v[212:215], v203 offset:19456
	ds_read_b128 v[216:219], v203 offset:20480
	ds_read_b128 v[220:223], v203 offset:21504
	ds_read_b128 v[224:227], v203 offset:22528
	ds_read_b128 v[228:231], v203 offset:23552
	global_load_lds_dwordx4 v[232:233], off
	s_add_i32 m0, s39, 0x2000
	v_lshl_add_u64 v[234:235], s[54:55], 0, v[156:157]
	s_add_u32 s54, s54, s24
	s_addc_u32 s55, s55, 0
	s_add_i32 s15, s15, s25
	global_load_lds_dwordx4 v[234:235], off
	v_lshl_add_u64 v[236:237], s[54:55], 0, v[152:153]
	s_mov_b32 m0, s15
	v_lshl_add_u64 v[238:239], s[54:55], 0, v[156:157]
	global_load_lds_dwordx4 v[236:237], off
	s_add_i32 m0, s15, 0x2000
	v_lshl_add_u64 v[240:241], s[12:13], 0, v[150:151]
	global_load_lds_dwordx4 v[238:239], off
	s_mov_b32 m0, s70
	v_lshl_add_u64 v[242:243], s[12:13], 0, v[154:155]
	global_load_lds_dwordx4 v[240:241], off
	s_mov_b32 m0, s71
	s_nop 0
	global_load_lds_dwordx4 v[242:243], off
	s_waitcnt vmcnt(8)
	s_waitcnt lgkmcnt(0)
	s_barrier
; #define PG8_STAGE(bufoff, gbase, voff) do { _Pragma("unroll") for (int _i = 0; _i < 2; ++_i) \
;         __builtin_amdgcn_global_load_lds((const unsigned*)((const char*)(gbase) + (voff)[_i]), (LAS unsigned*)(lds + (bufoff) + ldsw + _i * 8192), 16, 0, 0); } while (0)
; #define PG8_LDA(dst, b, h) do { _Pragma("unroll") for (int m = 0; m < 4; ++m) _Pragma("unroll") for (int k = 0; k < 2; ++k) dst[m][k] = *(const LAS bf16x8*)(lds + PG8_SA(b, h) + aoff + m * 2048 + k * 1024); } while (0)
; #define PG8_LDB(dst, b, h) do { _Pragma("unroll") for (int n = 0; n < 2; ++n) _Pragma("unroll") for (int k = 0; k < 2; ++k) dst[n][k] = *(const LAS bf16x8*)(lds + PG8_SB(b, h) + boff + n * 2048 + k * 1024); } while (0)
; #define PG8_MMA(ai, bj, At, Bt) do { __builtin_amdgcn_s_setprio(1); _Pragma("unroll") for (int m = 0; m < 4; ++m) _Pragma("unroll") for (int n = 0; n < 2; ++n) _Pragma("unroll") for (int k = 0; k < 2; ++k) \
;         acc[ai][bj][m][n] = __builtin_amdgcn_mfma_f32_16x16x32_bf16(Bt[n][k], At[m][k], acc[ai][bj][m][n], 0, 0, 0); __builtin_amdgcn_s_setprio(0); } while (0)
; #define PG8_WAIT_V(n) asm volatile("s_waitcnt vmcnt(" #n ")" ::: "memory")
; #define PG8_WAIT_L(n) asm volatile("s_waitcnt lgkmcnt(" #n ")" ::: "memory")
; #define PG8_BAR __builtin_amdgcn_s_barrier()
; #define PG8_SCHED __builtin_amdgcn_sched_barrier(0)
; template <class Epi, class Sched>
; __device__ __forceinline__ void gemm_phase(LAS unsigned char* lds, const Gemm g, const Sched& S, const Epi& E, const int tid) {
;     ...
;             PG8_WAIT_V(8); PG8_WAIT_L(0); PG8_BAR; PG8_MMA(1, 0, At, B0); PG8_MMA(1, 1, At, B1); PG8_BAR; PG8_SCHED;
;             PG8_LDB(B0, 1, 0); PG8_LDB(B1, 1, 1); PG8_SCHED; PG8_LDA(At, 1, 0); PG8_STAGE(PG8_SA(0, 1), a2 + hstep, voffA);
;             PG8_WAIT_V(8); PG8_WAIT_L(0); PG8_BAR; PG8_MMA(0, 0, At, B0); PG8_MMA(0, 1, At, B1); PG8_BAR; PG8_SCHED;
;             PG8_LDA(At, 1, 1); PG8_STAGE(PG8_SB(1, 0), b3, voffB); PG8_STAGE(PG8_SB(1, 1), b3 + hstep, voffB); PG8_STAGE(PG8_SA(1, 0), a3, voffA);
	s_setprio 1
	s_waitcnt lgkmcnt(0)
	v_mfma_f32_16x16x32_bf16 v[60:63], v[128:131], v[182:185], 0
	v_mfma_f32_16x16x32_bf16 v[56:59], v[136:139], v[182:185], 0
	v_mfma_f32_16x16x32_bf16 v[44:47], v[128:131], v[208:211], 0
	v_mfma_f32_16x16x32_bf16 v[40:43], v[136:139], v[208:211], 0
	v_mfma_f32_16x16x32_bf16 v[28:31], v[128:131], v[216:219], 0
	v_mfma_f32_16x16x32_bf16 v[24:27], v[136:139], v[216:219], 0
	v_mfma_f32_16x16x32_bf16 v[12:15], v[128:131], v[224:227], 0
	v_mfma_f32_16x16x32_bf16 v[8:11], v[136:139], v[224:227], 0
	v_mfma_f32_16x16x32_bf16 v[60:63], v[132:135], v[204:207], v[60:63]
	v_mfma_f32_16x16x32_bf16 v[56:59], v[140:143], v[204:207], v[56:59]
	v_mfma_f32_16x16x32_bf16 v[44:47], v[132:135], v[212:215], v[44:47]
	v_mfma_f32_16x16x32_bf16 v[40:43], v[140:143], v[212:215], v[40:43]
	v_mfma_f32_16x16x32_bf16 v[28:31], v[132:135], v[220:223], v[28:31]
	v_mfma_f32_16x16x32_bf16 v[24:27], v[140:143], v[220:223], v[24:27]
	v_mfma_f32_16x16x32_bf16 v[12:15], v[132:135], v[228:231], v[12:15]
	v_mfma_f32_16x16x32_bf16 v[8:11], v[140:143], v[228:231], v[8:11]
	s_setprio 0
	s_setprio 1
	v_mfma_f32_16x16x32_bf16 v[52:55], v[166:169], v[182:185], 0
	v_mfma_f32_16x16x32_bf16 v[48:51], v[174:177], v[182:185], 0
	v_mfma_f32_16x16x32_bf16 v[36:39], v[166:169], v[208:211], 0
	v_mfma_f32_16x16x32_bf16 v[32:35], v[174:177], v[208:211], 0
	v_mfma_f32_16x16x32_bf16 v[20:23], v[166:169], v[216:219], 0
	v_mfma_f32_16x16x32_bf16 v[16:19], v[174:177], v[216:219], 0
	v_mfma_f32_16x16x32_bf16 v[4:7], v[166:169], v[224:227], 0
	v_mfma_f32_16x16x32_bf16 v[0:3], v[174:177], v[224:227], 0
	v_mfma_f32_16x16x32_bf16 v[52:55], v[170:173], v[204:207], v[52:55]
	v_mfma_f32_16x16x32_bf16 v[48:51], v[178:181], v[204:207], v[48:51]
	v_mfma_f32_16x16x32_bf16 v[36:39], v[170:173], v[212:215], v[36:39]
	v_mfma_f32_16x16x32_bf16 v[32:35], v[178:181], v[212:215], v[32:35]
	v_mfma_f32_16x16x32_bf16 v[20:23], v[170:173], v[220:223], v[20:23]
	v_mfma_f32_16x16x32_bf16 v[16:19], v[178:181], v[220:223], v[16:19]
	v_mfma_f32_16x16x32_bf16 v[4:7], v[170:173], v[228:231], v[4:7]
	v_mfma_f32_16x16x32_bf16 v[0:3], v[178:181], v[228:231], v[0:3]
	s_setprio 0
	s_barrier
	s_add_i32 s15, 0, 0x18000
	s_add_i32 s39, 0, 0x1c000
	v_add_u32_e32 v140, s15, v202
	v_add_u32_e32 v144, s39, v202
	ds_read_b128 v[128:131], v140
	ds_read_b128 v[132:135], v140 offset:1024
	ds_read_b128 v[136:139], v140 offset:2048
	ds_read_b128 v[140:143], v140 offset:3072
	ds_read_b128 v[166:169], v144
	ds_read_b128 v[170:173], v144 offset:1024
	ds_read_b128 v[174:177], v144 offset:2048
	ds_read_b128 v[178:181], v144 offset:3072
	s_add_u32 s12, s12, s24
	s_addc_u32 s13, s13, 0
	s_mov_b32 m0, s72
	v_lshl_add_u64 v[244:245], s[12:13], 0, v[150:151]
	ds_read_b128 v[182:185], v203 offset:32768
	ds_read_b128 v[204:207], v203 offset:33792
	ds_read_b128 v[208:211], v203 offset:34816
	ds_read_b128 v[212:215], v203 offset:35840
	ds_read_b128 v[216:219], v203 offset:36864
	ds_read_b128 v[220:223], v203 offset:37888
	ds_read_b128 v[224:227], v203 offset:38912
	ds_read_b128 v[228:231], v203 offset:39936
	global_load_lds_dwordx4 v[244:245], off
	v_lshl_add_u64 v[244:245], s[12:13], 0, v[154:155]
	s_mov_b32 m0, s73
	s_nop 0
	global_load_lds_dwordx4 v[244:245], off
	s_waitcnt vmcnt(8)
	s_waitcnt lgkmcnt(0)
	s_barrier
	s_setprio 1
	s_waitcnt lgkmcnt(0)
	v_mfma_f32_16x16x32_bf16 v[124:127], v[128:131], v[182:185], v[124:127]
	v_mfma_f32_16x16x32_bf16 v[120:123], v[136:139], v[182:185], v[120:123]
	v_mfma_f32_16x16x32_bf16 v[108:111], v[128:131], v[208:211], v[108:111]
	v_mfma_f32_16x16x32_bf16 v[104:107], v[136:139], v[208:211], v[104:107]
	v_mfma_f32_16x16x32_bf16 v[92:95], v[128:131], v[216:219], v[92:95]
	v_mfma_f32_16x16x32_bf16 v[88:91], v[136:139], v[216:219], v[88:91]
	v_mfma_f32_16x16x32_bf16 v[76:79], v[128:131], v[224:227], v[76:79]
	v_mfma_f32_16x16x32_bf16 v[72:75], v[136:139], v[224:227], v[72:75]
	v_mfma_f32_16x16x32_bf16 v[124:127], v[132:135], v[204:207], v[124:127]
	v_mfma_f32_16x16x32_bf16 v[120:123], v[140:143], v[204:207], v[120:123]
	v_mfma_f32_16x16x32_bf16 v[108:111], v[132:135], v[212:215], v[108:111]
	v_mfma_f32_16x16x32_bf16 v[104:107], v[140:143], v[212:215], v[104:107]
	v_mfma_f32_16x16x32_bf16 v[92:95], v[132:135], v[220:223], v[92:95]
	v_mfma_f32_16x16x32_bf16 v[88:91], v[140:143], v[220:223], v[88:91]
	v_mfma_f32_16x16x32_bf16 v[76:79], v[132:135], v[228:231], v[76:79]
	v_mfma_f32_16x16x32_bf16 v[72:75], v[140:143], v[228:231], v[72:75]
	s_setprio 0
	s_setprio 1
	v_mfma_f32_16x16x32_bf16 v[116:119], v[166:169], v[182:185], v[116:119]
	v_mfma_f32_16x16x32_bf16 v[112:115], v[174:177], v[182:185], v[112:115]
	v_mfma_f32_16x16x32_bf16 v[100:103], v[166:169], v[208:211], v[100:103]
	v_mfma_f32_16x16x32_bf16 v[96:99], v[174:177], v[208:211], v[96:99]
	v_mfma_f32_16x16x32_bf16 v[84:87], v[166:169], v[216:219], v[84:87]
	v_mfma_f32_16x16x32_bf16 v[80:83], v[174:177], v[216:219], v[80:83]
	v_mfma_f32_16x16x32_bf16 v[68:71], v[166:169], v[224:227], v[68:71]
	v_mfma_f32_16x16x32_bf16 v[64:67], v[174:177], v[224:227], v[64:67]
	v_mfma_f32_16x16x32_bf16 v[116:119], v[170:173], v[204:207], v[116:119]
	v_mfma_f32_16x16x32_bf16 v[112:115], v[178:181], v[204:207], v[112:115]
	v_mfma_f32_16x16x32_bf16 v[100:103], v[170:173], v[212:215], v[100:103]
	v_mfma_f32_16x16x32_bf16 v[96:99], v[178:181], v[212:215], v[96:99]
	v_mfma_f32_16x16x32_bf16 v[84:87], v[170:173], v[220:223], v[84:87]
	v_mfma_f32_16x16x32_bf16 v[80:83], v[178:181], v[220:223], v[80:83]
	v_mfma_f32_16x16x32_bf16 v[68:71], v[170:173], v[228:231], v[68:71]
	v_mfma_f32_16x16x32_bf16 v[64:67], v[178:181], v[228:231], v[64:67]
	s_setprio 0
	s_barrier
; #define PG8_STAGE(bufoff, gbase, voff) do { _Pragma("unroll") for (int _i = 0; _i < 2; ++_i) \
;         __builtin_amdgcn_global_load_lds((const unsigned*)((const char*)(gbase) + (voff)[_i]), (LAS unsigned*)(lds + (bufoff) + ldsw + _i * 8192), 16, 0, 0); } while (0)
; #define PG8_LDA(dst, b, h) do { _Pragma("unroll") for (int m = 0; m < 4; ++m) _Pragma("unroll") for (int k = 0; k < 2; ++k) dst[m][k] = *(const LAS bf16x8*)(lds + PG8_SA(b, h) + aoff + m * 2048 + k * 1024); } while (0)
; #define PG8_MMA(ai, bj, At, Bt) do { __builtin_amdgcn_s_setprio(1); _Pragma("unroll") for (int m = 0; m < 4; ++m) _Pragma("unroll") for (int n = 0; n < 2; ++n) _Pragma("unroll") for (int k = 0; k < 2; ++k) \
;         acc[ai][bj][m][n] = __builtin_amdgcn_mfma_f32_16x16x32_bf16(Bt[n][k], At[m][k], acc[ai][bj][m][n], 0, 0, 0); __builtin_amdgcn_s_setprio(0); } while (0)
; #define PG8_WAIT_V(n) asm volatile("s_waitcnt vmcnt(" #n ")" ::: "memory")
; #define PG8_WAIT_L(n) asm volatile("s_waitcnt lgkmcnt(" #n ")" ::: "memory")
; #define PG8_BAR __builtin_amdgcn_s_barrier()
; #define PG8_SCHED __builtin_amdgcn_sched_barrier(0)
; template <class Epi, class Sched>
; __device__ __forceinline__ void gemm_phase(LAS unsigned char* lds, const Gemm g, const Sched& S, const Epi& E, const int tid) {
;     ...
;         for (int t = 0; t < nt; t += 2) {
;     ...
;             PG8_LDA(At, 1, 1); PG8_STAGE(PG8_SB(1, 0), b3, voffB); PG8_STAGE(PG8_SB(1, 1), b3 + hstep, voffB); PG8_STAGE(PG8_SA(1, 0), a3, voffA);
;             PG8_WAIT_V(8); PG8_WAIT_L(0); PG8_BAR; PG8_MMA(1, 0, At, B0); PG8_MMA(1, 1, At, B1); PG8_BAR; PG8_SCHED;
	s_add_i32 s12, s15, s25
	v_lshl_add_u64 v[232:233], v[232:233], 0, s[84:85]
	s_mov_b32 m0, s12
	ds_read_b128 v[182:185], v203 offset:49152
	ds_read_b128 v[204:207], v203 offset:50176
	ds_read_b128 v[208:211], v203 offset:51200
	ds_read_b128 v[212:215], v203 offset:52224
	ds_read_b128 v[216:219], v203 offset:53248
	ds_read_b128 v[220:223], v203 offset:54272
	ds_read_b128 v[224:227], v203 offset:55296
	ds_read_b128 v[228:231], v203 offset:56320
	global_load_lds_dwordx4 v[232:233], off
	v_lshl_add_u64 v[232:233], v[234:235], 0, s[84:85]
	s_add_i32 m0, s12, 0x2000
	s_add_i32 s12, s39, s25
	global_load_lds_dwordx4 v[232:233], off
	v_lshl_add_u64 v[232:233], v[236:237], 0, s[84:85]
	s_mov_b32 m0, s12
	s_nop 0
	global_load_lds_dwordx4 v[232:233], off
	v_lshl_add_u64 v[232:233], v[238:239], 0, s[84:85]
	s_add_i32 m0, s12, 0x2000
	s_nop 0
	global_load_lds_dwordx4 v[232:233], off
	v_lshl_add_u64 v[232:233], v[240:241], 0, s[84:85]
	s_mov_b32 m0, s3
	s_nop 0
	global_load_lds_dwordx4 v[232:233], off
	v_lshl_add_u64 v[232:233], v[242:243], 0, s[84:85]
	s_mov_b32 m0, s83
	s_nop 0
	global_load_lds_dwordx4 v[232:233], off
	s_waitcnt vmcnt(8)
	s_waitcnt lgkmcnt(0)
	s_barrier
	s_setprio 1
	s_waitcnt lgkmcnt(0)
	v_mfma_f32_16x16x32_bf16 v[60:63], v[128:131], v[182:185], v[60:63]
	v_mfma_f32_16x16x32_bf16 v[56:59], v[136:139], v[182:185], v[56:59]
	v_mfma_f32_16x16x32_bf16 v[44:47], v[128:131], v[208:211], v[44:47]
	v_mfma_f32_16x16x32_bf16 v[40:43], v[136:139], v[208:211], v[40:43]
	v_mfma_f32_16x16x32_bf16 v[28:31], v[128:131], v[216:219], v[28:31]
	v_mfma_f32_16x16x32_bf16 v[24:27], v[136:139], v[216:219], v[24:27]
	v_mfma_f32_16x16x32_bf16 v[12:15], v[128:131], v[224:227], v[12:15]
	v_mfma_f32_16x16x32_bf16 v[8:11], v[136:139], v[224:227], v[8:11]
	v_mfma_f32_16x16x32_bf16 v[60:63], v[132:135], v[204:207], v[60:63]
	v_mfma_f32_16x16x32_bf16 v[56:59], v[140:143], v[204:207], v[56:59]
	v_mfma_f32_16x16x32_bf16 v[44:47], v[132:135], v[212:215], v[44:47]
	v_mfma_f32_16x16x32_bf16 v[40:43], v[140:143], v[212:215], v[40:43]
	v_mfma_f32_16x16x32_bf16 v[28:31], v[132:135], v[220:223], v[28:31]
	v_mfma_f32_16x16x32_bf16 v[24:27], v[140:143], v[220:223], v[24:27]
	v_mfma_f32_16x16x32_bf16 v[12:15], v[132:135], v[228:231], v[12:15]
	v_mfma_f32_16x16x32_bf16 v[8:11], v[140:143], v[228:231], v[8:11]
	s_setprio 0
	s_setprio 1
	v_mfma_f32_16x16x32_bf16 v[52:55], v[166:169], v[182:185], v[52:55]
	v_mfma_f32_16x16x32_bf16 v[48:51], v[174:177], v[182:185], v[48:51]
	v_mfma_f32_16x16x32_bf16 v[36:39], v[166:169], v[208:211], v[36:39]
	v_mfma_f32_16x16x32_bf16 v[32:35], v[174:177], v[208:211], v[32:35]
	v_mfma_f32_16x16x32_bf16 v[20:23], v[166:169], v[216:219], v[20:23]
	v_mfma_f32_16x16x32_bf16 v[16:19], v[174:177], v[216:219], v[16:19]
	v_mfma_f32_16x16x32_bf16 v[4:7], v[166:169], v[224:227], v[4:7]
	v_mfma_f32_16x16x32_bf16 v[0:3], v[174:177], v[224:227], v[0:3]
	v_mfma_f32_16x16x32_bf16 v[52:55], v[170:173], v[204:207], v[52:55]
	v_mfma_f32_16x16x32_bf16 v[48:51], v[178:181], v[204:207], v[48:51]
	v_mfma_f32_16x16x32_bf16 v[36:39], v[170:173], v[212:215], v[36:39]
	v_mfma_f32_16x16x32_bf16 v[32:35], v[178:181], v[212:215], v[32:35]
	v_mfma_f32_16x16x32_bf16 v[20:23], v[170:173], v[220:223], v[20:23]
	v_mfma_f32_16x16x32_bf16 v[16:19], v[178:181], v[220:223], v[16:19]
	v_mfma_f32_16x16x32_bf16 v[4:7], v[170:173], v[228:231], v[4:7]
	v_mfma_f32_16x16x32_bf16 v[0:3], v[178:181], v[228:231], v[0:3]
	s_setprio 0
	s_barrier
	s_add_u32 s28, s28, 0x100
	s_addc_u32 s29, s29, 0
	s_add_u32 s10, s10, 0x100
	s_addc_u32 s11, s11, 0
	s_cmp_ge_u32 s14, s89
	s_mov_b32 s12, s14
	s_cbranch_scc1 .Lgemm_kdone

; #define PG8_BAR __builtin_amdgcn_s_barrier()
; template <class Epi, class Sched>
; __device__ __forceinline__ void gemm_phase(LAS unsigned char* lds, const Gemm g, const Sched& S, const Epi& E, const int tid) {
;     ...
;         }
;         if (wr == 0) PG8_BAR;
;         E(acc, cur, wr, wc, fr, fq);
.Lgemm_kdone:
	s_and_b64 vcc, exec, s[20:21]
	s_cbranch_vccz .LBB0_247
	s_barrier
